# XCD-last leaders poll their TOP replica immediately after bumping it (sleep 8 after each poll instead of 24 before)
# baseline (speedup 1.0000x reference)
.Lgb1_tloop:
	global_load_dword v4, v0, s[6:7] sc1
	s_add_u32 s13, s13, 1
	s_waitcnt vmcnt(0)
	v_readfirstlane_b32 s12, v4
	s_nop 3
	s_cmp_gt_u32 s13, 0x80000
	s_cbranch_scc1 .Lgb1_done
	s_cmp_ge_u32 s12, s11
	s_cbranch_scc1 .Lgb1_done
	s_sleep 8
	s_branch .Lgb1_tloop
